# grid barrier: the per-CU invalidate is issued right behind the arrival atomic and runs under the rest of the protocol
# speedup vs baseline: 1.0054x; 1.0054x over previous
.LBB0_670:
	s_or_b64 exec, exec, s[4:5]
	v_readlane_b32 s0, v247, 25
	v_readlane_b32 s1, v247, 26
	v_cvt_f32_u32_e32 v1, v2
	v_sub_u32_e32 v4, 0, v2
	v_rcp_iflag_f32_e32 v1, v1
	s_nop 1
	global_atomic_add v3, v153, v185, s[0:1] sc0
	v_readlane_b32 s4, v247, 61
	s_cmp_eq_u32 s4, 0
	s_cbranch_scc1 .Lno_cu_inv
	buffer_inv sc1
.Lno_cu_inv:
	v_mul_f32_e32 v1, 0x4f7ffffe, v1
	v_cvt_u32_f32_e32 v1, v1
	v_mul_lo_u32 v4, v4, v1
	v_mul_hi_u32 v4, v1, v4
	v_add_u32_e32 v1, v1, v4
	s_cmp_eq_u32 s4, 0
	s_cbranch_scc1 .Lcu_w0
	s_waitcnt vmcnt(1)
	s_branch .Lcu_w1

.Lcu_w1:
	v_mul_hi_u32 v1, v3, v1
	v_mul_lo_u32 v4, v1, v2
	v_sub_u32_e32 v4, v3, v4
	v_cmp_ge_u32_e32 vcc, v4, v2
	v_add_u32_e32 v5, 1, v1
	s_nop 0
	v_cndmask_b32_e32 v1, v1, v5, vcc
	v_sub_u32_e32 v5, v4, v2
	v_cndmask_b32_e32 v4, v4, v5, vcc
	v_cmp_ge_u32_e32 vcc, v4, v2
	v_add_u32_e32 v4, 1, v1
	s_nop 0
	v_cndmask_b32_e32 v1, v1, v4, vcc
	v_add_u32_e32 v4, 1, v3
	v_mad_u64_u32 v[2:3], s[0:1], v2, v1, v[2:3]
	v_cmp_ne_u32_e32 vcc, v4, v2
	s_and_saveexec_b64 s[0:1], vcc
	s_xor_b64 s[4:5], exec, s[0:1]
	s_cbranch_execz .LBB0_684
	v_readlane_b32 s0, v247, 27
	v_readlane_b32 s1, v247, 28
	s_nop 4
	global_load_dword v0, v153, s[0:1] sc1
	s_waitcnt vmcnt(0)
	v_cmp_eq_u32_e32 vcc, v0, v1
	s_and_saveexec_b64 s[0:1], vcc
	s_cbranch_execz .LBB0_683
	s_mov_b32 s12, 1
	s_mov_b64 s[6:7], 0
	s_branch .LBB0_674
